# Ph8 epilogue: ssq partial loads prefetched three rounds ahead
# speedup vs baseline: 1.0028x; 1.0028x over previous
.LBB0_1069:
	v_lshl_add_u32 v138, s23, 8, v143
	v_ashrrev_i32_e32 v139, 31, v138
	v_lshlrev_b64 v[148:149], 6, v[138:139]
	v_lshl_add_u64 v[174:175], s[46:47], 0, v[148:149]
	v_mov_b64_e32 v[248:249], v[174:175]
	v_mov_b32_e32 v204, 0x2000
	v_mov_b32_e32 v205, 0
	v_lshl_add_u64 v[250:251], v[248:249], 0, v[204:205]
	global_load_dwordx4 v[180:183], v[248:249], off
	global_load_dwordx4 v[184:187], v[248:249], off offset:16
	global_load_dwordx4 v[188:191], v[248:249], off offset:32
	global_load_dwordx4 v[192:195], v[248:249], off offset:48
	global_load_dwordx4 v[196:199], v[248:249], off offset:1024
	global_load_dwordx4 v[200:203], v[248:249], off offset:1040
	global_load_dwordx4 v[220:223], v[248:249], off offset:1056
	global_load_dwordx4 v[244:247], v[248:249], off offset:1072
	global_load_dwordx4 v[228:231], v[248:249], off offset:2048
	global_load_dwordx4 v[232:235], v[248:249], off offset:2064
	global_load_dwordx4 v[236:239], v[248:249], off offset:2080
	global_load_dwordx4 v[240:243], v[248:249], off offset:2096
	s_waitcnt vmcnt(8)
	v_mov_b64_e32 v[156:157], v[180:181]
	v_mov_b64_e32 v[158:159], v[182:183]
	v_mov_b64_e32 v[148:149], v[184:185]
	v_mov_b64_e32 v[150:151], v[186:187]
	v_mov_b64_e32 v[174:175], v[188:189]
	v_mov_b64_e32 v[176:177], v[190:191]
	v_mov_b64_e32 v[152:153], v[192:193]
	v_mov_b64_e32 v[154:155], v[194:195]
	global_load_dwordx4 v[180:183], v[248:249], off offset:3072
	global_load_dwordx4 v[184:187], v[248:249], off offset:3088
	global_load_dwordx4 v[188:191], v[248:249], off offset:3104
	global_load_dwordx4 v[192:195], v[248:249], off offset:3120
	s_nop 0
	v_lshl_or_b32 v140, s22, 7, v145
	v_ashrrev_i32_e32 v141, 31, v140
	s_mov_b64 s[58:59], -1
	s_mov_b64 s[30:31], s[34:35]
	v_mov_b32_e32 v178, v156
	v_mov_b32_e32 v179, v174
	v_mov_b32_e32 v174, v157
	v_pk_add_f32 v[156:157], v[178:179], v[174:175]
	v_mov_b32_e32 v174, v158
	v_mov_b32_e32 v175, v176
	v_mov_b32_e32 v176, v159
	v_pk_add_f32 v[158:159], v[174:175], v[176:177]
	s_nop 0
	v_pk_add_f32 v[156:157], v[156:157], v[158:159]
	v_mov_b32_e32 v158, v148
	v_mov_b32_e32 v159, v152
	v_mov_b32_e32 v152, v149
	v_pk_add_f32 v[148:149], v[158:159], v[152:153]
	v_mov_b32_e32 v152, v150
	v_mov_b32_e32 v153, v154
	v_mov_b32_e32 v154, v151
	v_pk_add_f32 v[150:151], v[152:153], v[154:155]
	s_nop 0
	v_pk_add_f32 v[148:149], v[148:149], v[150:151]
	s_nop 0
	v_pk_add_f32 v[148:149], v[156:157], v[148:149]
	s_nop 0
	v_add_f32_e32 v139, v148, v149
	v_fmamk_f32 v139, v139, 0x3a800000, v206
	v_cmp_gt_f32_e32 vcc, s11, v139
	v_mul_f32_e32 v142, 0x4b800000, v139
	s_nop 0
	v_cndmask_b32_e32 v139, v139, v142, vcc
	v_rsq_f32_e32 v139, v139
	s_nop 0
	v_mul_f32_e32 v142, 0x45800000, v139
	v_cndmask_b32_e32 v142, v139, v142, vcc
	v_pk_mul_f32 v[124:125], v[124:125], v[142:143] op_sel_hi:[1,0]
	v_pk_mul_f32 v[120:121], v[120:121], v[142:143] op_sel_hi:[1,0]
	v_mul_f32_e32 v139, 0xbfb8aa3b, v124
	v_exp_f32_e32 v139, v139
	v_pk_mul_f32 v[122:123], v[122:123], v[142:143] op_sel_hi:[1,0]
	v_pk_mul_f32 v[116:117], v[116:117], v[142:143] op_sel_hi:[1,0]
	v_pk_mul_f32 v[112:113], v[112:113], v[142:143] op_sel_hi:[1,0]
	v_add_f32_e32 v139, 1.0, v139
	v_rcp_f32_e32 v148, v139
	v_mul_f32_e32 v139, 0xbfb8aa3b, v125
	v_exp_f32_e32 v139, v139
	v_pk_mul_f32 v[114:115], v[114:115], v[142:143] op_sel_hi:[1,0]
	v_add_f32_e32 v139, 1.0, v139
	v_rcp_f32_e32 v149, v139
	s_nop 0
	v_pk_mul_f32 v[124:125], v[124:125], v[148:149]
	s_nop 0
	v_pk_mul_f32 v[120:121], v[120:121], v[124:125]
	v_pk_mul_f32 v[124:125], v[126:127], v[142:143] op_sel_hi:[1,0]
	s_nop 0
	v_mul_f32_e32 v126, 0xbfb8aa3b, v124
	v_mul_f32_e32 v127, 0xbfb8aa3b, v125
	v_exp_f32_e32 v126, v126
	v_exp_f32_e32 v127, v127
	v_add_f32_e32 v126, 1.0, v126
	v_add_f32_e32 v127, 1.0, v127
	v_rcp_f32_e32 v126, v126
	v_rcp_f32_e32 v127, v127
	s_nop 0
	v_pk_mul_f32 v[124:125], v[124:125], v[126:127]
	s_nop 0
	v_pk_mul_f32 v[122:123], v[122:123], v[124:125]
	v_cvt_pk_bf16_f32 v124, v120, v121
	v_mov_b64_e32 v[120:121], s[44:45]
	v_cvt_pk_bf16_f32 v125, v122, v123
	v_mad_i64_i32 v[126:127], s[6:7], v138, s16, v[120:121]
	v_lshlrev_b64 v[122:123], 1, v[140:141]
	v_lshl_add_u64 v[126:127], v[126:127], 0, v[122:123]
	global_store_dwordx2 v[126:127], v[124:125], off
	v_mul_f32_e32 v124, 0xbfb8aa3b, v116
	v_mul_f32_e32 v125, 0xbfb8aa3b, v117
	v_exp_f32_e32 v124, v124
	v_exp_f32_e32 v125, v125
	v_add_f32_e32 v124, 1.0, v124
	v_add_f32_e32 v125, 1.0, v125
	v_rcp_f32_e32 v124, v124
	v_rcp_f32_e32 v125, v125
	s_nop 0
	v_pk_mul_f32 v[116:117], v[116:117], v[124:125]
	s_nop 0
	v_pk_mul_f32 v[112:113], v[112:113], v[116:117]
	v_pk_mul_f32 v[116:117], v[118:119], v[142:143] op_sel_hi:[1,0]
	v_or_b32_e32 v124, 16, v138
	v_mul_f32_e32 v118, 0xbfb8aa3b, v116
	v_mul_f32_e32 v119, 0xbfb8aa3b, v117
	v_exp_f32_e32 v118, v118
	v_exp_f32_e32 v119, v119
	v_cvt_pk_bf16_f32 v112, v112, v113
	v_ashrrev_i32_e32 v125, 31, v124
	v_add_f32_e32 v118, 1.0, v118
	v_add_f32_e32 v119, 1.0, v119
	v_rcp_f32_e32 v118, v118
	v_rcp_f32_e32 v119, v119
	s_nop 0
	v_pk_mul_f32 v[116:117], v[116:117], v[118:119]
	s_nop 0
	v_pk_mul_f32 v[114:115], v[114:115], v[116:117]
	s_nop 0
	v_cvt_pk_bf16_f32 v113, v114, v115
	global_store_dwordx2 v[126:127], v[112:113], off offset:128
	v_lshlrev_b64 v[112:113], 6, v[124:125]
	v_lshl_add_u64 v[126:127], s[46:47], 0, v[112:113]
	s_waitcnt vmcnt(10)
	v_mov_b64_e32 v[148:149], v[196:197]
	v_mov_b64_e32 v[150:151], v[198:199]
	v_mov_b64_e32 v[112:113], v[200:201]
	v_mov_b64_e32 v[114:115], v[202:203]
	v_mov_b64_e32 v[152:153], v[220:221]
	v_mov_b64_e32 v[154:155], v[222:223]
	v_mov_b64_e32 v[116:117], v[244:245]
	v_mov_b64_e32 v[118:119], v[246:247]
	global_load_dwordx4 v[196:199], v[250:251], off
	global_load_dwordx4 v[200:203], v[250:251], off offset:16
	global_load_dwordx4 v[220:223], v[250:251], off offset:32
	global_load_dwordx4 v[244:247], v[250:251], off offset:48
	v_mov_b32_e32 v126, v148
	v_mov_b32_e32 v127, v152
	v_mov_b32_e32 v152, v149
	v_mov_b32_e32 v140, v150
	v_mov_b32_e32 v141, v154
	v_mov_b32_e32 v154, v151
	v_pk_add_f32 v[126:127], v[126:127], v[152:153]
	v_pk_add_f32 v[140:141], v[140:141], v[154:155]
	s_nop 0
	v_pk_add_f32 v[126:127], v[126:127], v[140:141]
	v_mov_b32_e32 v140, v112
	v_mov_b32_e32 v141, v116
	v_mov_b32_e32 v116, v113
	v_pk_add_f32 v[112:113], v[140:141], v[116:117]
	v_mov_b32_e32 v116, v114
	v_mov_b32_e32 v117, v118
	v_mov_b32_e32 v118, v115
	v_pk_add_f32 v[114:115], v[116:117], v[118:119]
	s_nop 0
	v_pk_add_f32 v[112:113], v[112:113], v[114:115]
	s_nop 0
	v_pk_add_f32 v[112:113], v[126:127], v[112:113]
	s_nop 0
	v_add_f32_e32 v112, v112, v113
	v_fmamk_f32 v112, v112, 0x3a800000, v206
	v_cmp_gt_f32_e32 vcc, s11, v112
	v_mul_f32_e32 v113, 0x4b800000, v112
	s_nop 0
	v_cndmask_b32_e32 v112, v112, v113, vcc
	v_rsq_f32_e32 v112, v112
	s_nop 0
	v_mul_f32_e32 v113, 0x45800000, v112
	v_cndmask_b32_e32 v112, v112, v113, vcc
	v_pk_mul_f32 v[108:109], v[108:109], v[112:113] op_sel_hi:[1,0]
	s_nop 0
	v_mul_f32_e32 v113, 0xbfb8aa3b, v108
	v_exp_f32_e32 v113, v113
	s_nop 0
	v_add_f32_e32 v113, 1.0, v113
	v_rcp_f32_e32 v114, v113
	v_mul_f32_e32 v113, 0xbfb8aa3b, v109
	v_exp_f32_e32 v113, v113
	s_nop 0
	v_add_f32_e32 v113, 1.0, v113
	v_rcp_f32_e32 v115, v113
	v_pk_mul_f32 v[104:105], v[104:105], v[112:113] op_sel_hi:[1,0]
	v_pk_mul_f32 v[106:107], v[106:107], v[112:113] op_sel_hi:[1,0]
	v_pk_mul_f32 v[100:101], v[100:101], v[112:113] op_sel_hi:[1,0]
	v_pk_mul_f32 v[108:109], v[108:109], v[114:115]
	v_pk_mul_f32 v[96:97], v[96:97], v[112:113] op_sel_hi:[1,0]
	v_pk_mul_f32 v[104:105], v[104:105], v[108:109]
	v_pk_mul_f32 v[108:109], v[110:111], v[112:113] op_sel_hi:[1,0]
	v_cvt_pk_bf16_f32 v104, v104, v105
	v_mul_f32_e32 v110, 0xbfb8aa3b, v108
	v_mul_f32_e32 v111, 0xbfb8aa3b, v109
	v_exp_f32_e32 v110, v110
	v_exp_f32_e32 v111, v111
	v_pk_mul_f32 v[98:99], v[98:99], v[112:113] op_sel_hi:[1,0]
	v_add_f32_e32 v110, 1.0, v110
	v_add_f32_e32 v111, 1.0, v111
	v_rcp_f32_e32 v110, v110
	v_rcp_f32_e32 v111, v111
	s_nop 0
	v_pk_mul_f32 v[108:109], v[108:109], v[110:111]
	s_nop 0
	v_pk_mul_f32 v[106:107], v[106:107], v[108:109]
	s_nop 0
	v_cvt_pk_bf16_f32 v105, v106, v107
	v_mad_i64_i32 v[106:107], s[6:7], v124, s16, v[120:121]
	v_lshl_add_u64 v[106:107], v[106:107], 0, v[122:123]
	global_store_dwordx2 v[106:107], v[104:105], off
	v_mul_f32_e32 v104, 0xbfb8aa3b, v100
	v_mul_f32_e32 v105, 0xbfb8aa3b, v101
	v_exp_f32_e32 v104, v104
	v_exp_f32_e32 v105, v105
	v_add_f32_e32 v104, 1.0, v104
	v_add_f32_e32 v105, 1.0, v105
	v_rcp_f32_e32 v104, v104
	v_rcp_f32_e32 v105, v105
	s_nop 0
	v_pk_mul_f32 v[100:101], v[100:101], v[104:105]
	s_nop 0
	v_pk_mul_f32 v[96:97], v[96:97], v[100:101]
	v_pk_mul_f32 v[100:101], v[102:103], v[112:113] op_sel_hi:[1,0]
	v_or_b32_e32 v104, 32, v138
	v_mul_f32_e32 v102, 0xbfb8aa3b, v100
	v_mul_f32_e32 v103, 0xbfb8aa3b, v101
	v_exp_f32_e32 v102, v102
	v_exp_f32_e32 v103, v103
	v_cvt_pk_bf16_f32 v96, v96, v97
	v_ashrrev_i32_e32 v105, 31, v104
	v_add_f32_e32 v102, 1.0, v102
	v_add_f32_e32 v103, 1.0, v103
	v_rcp_f32_e32 v102, v102
	v_rcp_f32_e32 v103, v103
	s_nop 0
	v_pk_mul_f32 v[100:101], v[100:101], v[102:103]
	s_nop 0
	v_pk_mul_f32 v[98:99], v[98:99], v[100:101]
	s_nop 0
	v_cvt_pk_bf16_f32 v97, v98, v99
	global_store_dwordx2 v[106:107], v[96:97], off offset:128
	v_lshlrev_b64 v[96:97], 6, v[104:105]
	v_lshl_add_u64 v[110:111], s[46:47], 0, v[96:97]
	s_waitcnt vmcnt(12)
	v_mov_b64_e32 v[106:107], v[228:229]
	v_mov_b64_e32 v[108:109], v[230:231]
	v_mov_b64_e32 v[96:97], v[232:233]
	v_mov_b64_e32 v[98:99], v[234:235]
	v_mov_b64_e32 v[110:111], v[236:237]
	v_mov_b64_e32 v[112:113], v[238:239]
	v_mov_b64_e32 v[100:101], v[240:241]
	v_mov_b64_e32 v[102:103], v[242:243]
	global_load_dwordx4 v[228:231], v[250:251], off offset:1024
	global_load_dwordx4 v[232:235], v[250:251], off offset:1040
	global_load_dwordx4 v[236:239], v[250:251], off offset:1056
	global_load_dwordx4 v[240:243], v[250:251], off offset:1072
	s_nop 0
	v_mov_b32_e32 v114, v106
	v_mov_b32_e32 v115, v110
	v_mov_b32_e32 v110, v107
	v_pk_add_f32 v[106:107], v[114:115], v[110:111]
	v_mov_b32_e32 v110, v108
	v_mov_b32_e32 v111, v112
	v_mov_b32_e32 v112, v109
	v_pk_add_f32 v[108:109], v[110:111], v[112:113]
	s_nop 0
	v_pk_add_f32 v[106:107], v[106:107], v[108:109]
	v_mov_b32_e32 v108, v96
	v_mov_b32_e32 v109, v100
	v_mov_b32_e32 v100, v97
	v_pk_add_f32 v[96:97], v[108:109], v[100:101]
	v_mov_b32_e32 v100, v98
	v_mov_b32_e32 v101, v102
	v_mov_b32_e32 v102, v99
	v_pk_add_f32 v[98:99], v[100:101], v[102:103]
	s_nop 0
	v_pk_add_f32 v[96:97], v[96:97], v[98:99]
	s_nop 0
	v_pk_add_f32 v[96:97], v[106:107], v[96:97]
	s_nop 0
	v_add_f32_e32 v96, v96, v97
	v_fmamk_f32 v96, v96, 0x3a800000, v206
	v_cmp_gt_f32_e32 vcc, s11, v96
	v_mul_f32_e32 v97, 0x4b800000, v96
	s_nop 0
	v_cndmask_b32_e32 v96, v96, v97, vcc
	v_rsq_f32_e32 v96, v96
	s_nop 0
	v_mul_f32_e32 v97, 0x45800000, v96
	v_cndmask_b32_e32 v96, v96, v97, vcc
	v_pk_mul_f32 v[92:93], v[92:93], v[96:97] op_sel_hi:[1,0]
	s_nop 0
	v_mul_f32_e32 v97, 0xbfb8aa3b, v92
	v_exp_f32_e32 v97, v97
	s_nop 0
	v_add_f32_e32 v97, 1.0, v97
	v_rcp_f32_e32 v98, v97
	v_mul_f32_e32 v97, 0xbfb8aa3b, v93
	v_exp_f32_e32 v97, v97
	s_nop 0
	v_add_f32_e32 v97, 1.0, v97
	v_rcp_f32_e32 v99, v97
	v_pk_mul_f32 v[88:89], v[88:89], v[96:97] op_sel_hi:[1,0]
	v_pk_mul_f32 v[90:91], v[90:91], v[96:97] op_sel_hi:[1,0]
	v_pk_mul_f32 v[84:85], v[84:85], v[96:97] op_sel_hi:[1,0]
	v_pk_mul_f32 v[92:93], v[92:93], v[98:99]
	v_pk_mul_f32 v[80:81], v[80:81], v[96:97] op_sel_hi:[1,0]
	v_pk_mul_f32 v[88:89], v[88:89], v[92:93]
	v_pk_mul_f32 v[92:93], v[94:95], v[96:97] op_sel_hi:[1,0]
	v_cvt_pk_bf16_f32 v88, v88, v89
	v_mul_f32_e32 v94, 0xbfb8aa3b, v92
	v_mul_f32_e32 v95, 0xbfb8aa3b, v93
	v_exp_f32_e32 v94, v94
	v_exp_f32_e32 v95, v95
	v_pk_mul_f32 v[82:83], v[82:83], v[96:97] op_sel_hi:[1,0]
	v_add_f32_e32 v94, 1.0, v94
	v_add_f32_e32 v95, 1.0, v95
	v_rcp_f32_e32 v94, v94
	v_rcp_f32_e32 v95, v95
	s_nop 0
	v_pk_mul_f32 v[92:93], v[92:93], v[94:95]
	s_nop 0
	v_pk_mul_f32 v[90:91], v[90:91], v[92:93]
	s_nop 0
	v_cvt_pk_bf16_f32 v89, v90, v91
	v_mad_i64_i32 v[90:91], s[6:7], v104, s16, v[120:121]
	v_lshl_add_u64 v[90:91], v[90:91], 0, v[122:123]
	global_store_dwordx2 v[90:91], v[88:89], off
	v_mul_f32_e32 v88, 0xbfb8aa3b, v84
	v_mul_f32_e32 v89, 0xbfb8aa3b, v85
	v_exp_f32_e32 v88, v88
	v_exp_f32_e32 v89, v89
	v_add_f32_e32 v88, 1.0, v88
	v_add_f32_e32 v89, 1.0, v89
	v_rcp_f32_e32 v88, v88
	v_rcp_f32_e32 v89, v89
	s_nop 0
	v_pk_mul_f32 v[84:85], v[84:85], v[88:89]
	s_nop 0
	v_pk_mul_f32 v[80:81], v[80:81], v[84:85]
	v_pk_mul_f32 v[84:85], v[86:87], v[96:97] op_sel_hi:[1,0]
	v_or_b32_e32 v88, 48, v138
	v_mul_f32_e32 v86, 0xbfb8aa3b, v84
	v_mul_f32_e32 v87, 0xbfb8aa3b, v85
	v_exp_f32_e32 v86, v86
	v_exp_f32_e32 v87, v87
	v_cvt_pk_bf16_f32 v80, v80, v81
	v_ashrrev_i32_e32 v89, 31, v88
	v_add_f32_e32 v86, 1.0, v86
	v_add_f32_e32 v87, 1.0, v87
	v_rcp_f32_e32 v86, v86
	v_rcp_f32_e32 v87, v87
	s_nop 0
	v_pk_mul_f32 v[84:85], v[84:85], v[86:87]
	s_nop 0
	v_pk_mul_f32 v[82:83], v[82:83], v[84:85]
	s_nop 0
	v_cvt_pk_bf16_f32 v81, v82, v83
	global_store_dwordx2 v[90:91], v[80:81], off offset:128
	v_lshlrev_b64 v[80:81], 6, v[88:89]
	v_lshl_add_u64 v[94:95], s[46:47], 0, v[80:81]
	s_waitcnt vmcnt(14)
	v_mov_b64_e32 v[90:91], v[180:181]
	v_mov_b64_e32 v[92:93], v[182:183]
	v_mov_b64_e32 v[80:81], v[184:185]
	v_mov_b64_e32 v[82:83], v[186:187]
	v_mov_b64_e32 v[94:95], v[188:189]
	v_mov_b64_e32 v[96:97], v[190:191]
	v_mov_b64_e32 v[84:85], v[192:193]
	v_mov_b64_e32 v[86:87], v[194:195]
	global_load_dwordx4 v[180:183], v[250:251], off offset:2048
	global_load_dwordx4 v[184:187], v[250:251], off offset:2064
	global_load_dwordx4 v[188:191], v[250:251], off offset:2080
	global_load_dwordx4 v[192:195], v[250:251], off offset:2096
	s_nop 0
	v_mov_b32_e32 v98, v90
	v_mov_b32_e32 v99, v94
	v_mov_b32_e32 v94, v91
	v_pk_add_f32 v[90:91], v[98:99], v[94:95]
	v_mov_b32_e32 v94, v92
	v_mov_b32_e32 v95, v96
	v_mov_b32_e32 v96, v93
	v_pk_add_f32 v[92:93], v[94:95], v[96:97]
	s_nop 0
	v_pk_add_f32 v[90:91], v[90:91], v[92:93]
	v_mov_b32_e32 v92, v80
	v_mov_b32_e32 v93, v84
	v_mov_b32_e32 v84, v81
	v_pk_add_f32 v[80:81], v[92:93], v[84:85]
	v_mov_b32_e32 v84, v82
	v_mov_b32_e32 v85, v86
	v_mov_b32_e32 v86, v83
	v_pk_add_f32 v[82:83], v[84:85], v[86:87]
	s_nop 0
	v_pk_add_f32 v[80:81], v[80:81], v[82:83]
	s_nop 0
	v_pk_add_f32 v[80:81], v[90:91], v[80:81]
	s_nop 0
	v_add_f32_e32 v80, v80, v81
	v_fmamk_f32 v80, v80, 0x3a800000, v206
	v_cmp_gt_f32_e32 vcc, s11, v80
	v_mul_f32_e32 v81, 0x4b800000, v80
	s_nop 0
	v_cndmask_b32_e32 v80, v80, v81, vcc
	v_rsq_f32_e32 v80, v80
	s_nop 0
	v_mul_f32_e32 v81, 0x45800000, v80
	v_cndmask_b32_e32 v80, v80, v81, vcc
	v_pk_mul_f32 v[76:77], v[76:77], v[80:81] op_sel_hi:[1,0]
	s_nop 0
	v_mul_f32_e32 v81, 0xbfb8aa3b, v76
	v_exp_f32_e32 v81, v81
	s_nop 0
	v_add_f32_e32 v81, 1.0, v81
	v_rcp_f32_e32 v82, v81
	v_mul_f32_e32 v81, 0xbfb8aa3b, v77
	v_exp_f32_e32 v81, v81
	s_nop 0
	v_add_f32_e32 v81, 1.0, v81
	v_rcp_f32_e32 v83, v81
	v_pk_mul_f32 v[72:73], v[72:73], v[80:81] op_sel_hi:[1,0]
	v_pk_mul_f32 v[74:75], v[74:75], v[80:81] op_sel_hi:[1,0]
	v_pk_mul_f32 v[68:69], v[68:69], v[80:81] op_sel_hi:[1,0]
	v_pk_mul_f32 v[76:77], v[76:77], v[82:83]
	v_pk_mul_f32 v[64:65], v[64:65], v[80:81] op_sel_hi:[1,0]
	v_pk_mul_f32 v[72:73], v[72:73], v[76:77]
	v_pk_mul_f32 v[76:77], v[78:79], v[80:81] op_sel_hi:[1,0]
	v_cvt_pk_bf16_f32 v72, v72, v73
	v_mul_f32_e32 v78, 0xbfb8aa3b, v76
	v_mul_f32_e32 v79, 0xbfb8aa3b, v77
	v_exp_f32_e32 v78, v78
	v_exp_f32_e32 v79, v79
	v_pk_mul_f32 v[66:67], v[66:67], v[80:81] op_sel_hi:[1,0]
	v_add_f32_e32 v78, 1.0, v78
	v_add_f32_e32 v79, 1.0, v79
	v_rcp_f32_e32 v78, v78
	v_rcp_f32_e32 v79, v79
	s_nop 0
	v_pk_mul_f32 v[76:77], v[76:77], v[78:79]
	s_nop 0
	v_pk_mul_f32 v[74:75], v[74:75], v[76:77]
	s_nop 0
	v_cvt_pk_bf16_f32 v73, v74, v75
	v_mad_i64_i32 v[74:75], s[6:7], v88, s16, v[120:121]
	v_lshl_add_u64 v[74:75], v[74:75], 0, v[122:123]
	global_store_dwordx2 v[74:75], v[72:73], off
	v_mul_f32_e32 v72, 0xbfb8aa3b, v68
	v_mul_f32_e32 v73, 0xbfb8aa3b, v69
	v_exp_f32_e32 v72, v72
	v_exp_f32_e32 v73, v73
	v_add_f32_e32 v72, 1.0, v72
	v_add_f32_e32 v73, 1.0, v73
	v_rcp_f32_e32 v72, v72
	v_rcp_f32_e32 v73, v73
	s_nop 0
	v_pk_mul_f32 v[68:69], v[68:69], v[72:73]
	s_nop 0
	v_pk_mul_f32 v[64:65], v[64:65], v[68:69]
	v_pk_mul_f32 v[68:69], v[70:71], v[80:81] op_sel_hi:[1,0]
	v_add_u32_e32 v72, 0x80, v138
	v_mul_f32_e32 v70, 0xbfb8aa3b, v68
	v_mul_f32_e32 v71, 0xbfb8aa3b, v69
	v_exp_f32_e32 v70, v70
	v_exp_f32_e32 v71, v71
	v_cvt_pk_bf16_f32 v64, v64, v65
	v_ashrrev_i32_e32 v73, 31, v72
	v_add_f32_e32 v70, 1.0, v70
	v_add_f32_e32 v71, 1.0, v71
	v_rcp_f32_e32 v70, v70
	v_rcp_f32_e32 v71, v71
	s_nop 0
	v_pk_mul_f32 v[68:69], v[68:69], v[70:71]
	s_nop 0
	v_pk_mul_f32 v[66:67], v[66:67], v[68:69]
	s_nop 0
	v_cvt_pk_bf16_f32 v65, v66, v67
	global_store_dwordx2 v[74:75], v[64:65], off offset:128
	v_lshlrev_b64 v[64:65], 6, v[72:73]
	v_lshl_add_u64 v[78:79], s[46:47], 0, v[64:65]
	s_waitcnt vmcnt(14)
	v_mov_b64_e32 v[74:75], v[196:197]
	v_mov_b64_e32 v[76:77], v[198:199]
	v_mov_b64_e32 v[64:65], v[200:201]
	v_mov_b64_e32 v[66:67], v[202:203]
	v_mov_b64_e32 v[78:79], v[220:221]
	v_mov_b64_e32 v[80:81], v[222:223]
	v_mov_b64_e32 v[68:69], v[244:245]
	v_mov_b64_e32 v[70:71], v[246:247]
	global_load_dwordx4 v[196:199], v[250:251], off offset:3072
	global_load_dwordx4 v[200:203], v[250:251], off offset:3088
	global_load_dwordx4 v[220:223], v[250:251], off offset:3104
	global_load_dwordx4 v[244:247], v[250:251], off offset:3120
	s_nop 0
	v_mov_b32_e32 v82, v74
	v_mov_b32_e32 v83, v78
	v_mov_b32_e32 v78, v75
	v_pk_add_f32 v[74:75], v[82:83], v[78:79]
	v_mov_b32_e32 v78, v76
	v_mov_b32_e32 v79, v80
	v_mov_b32_e32 v80, v77
	v_pk_add_f32 v[76:77], v[78:79], v[80:81]
	s_nop 0
	v_pk_add_f32 v[74:75], v[74:75], v[76:77]
	v_mov_b32_e32 v76, v64
	v_mov_b32_e32 v77, v68
	v_mov_b32_e32 v68, v65
	v_pk_add_f32 v[64:65], v[76:77], v[68:69]
	v_mov_b32_e32 v68, v66
	v_mov_b32_e32 v69, v70
	v_mov_b32_e32 v70, v67
	v_pk_add_f32 v[66:67], v[68:69], v[70:71]
	s_nop 0
	v_pk_add_f32 v[64:65], v[64:65], v[66:67]
	s_nop 0
	v_pk_add_f32 v[64:65], v[74:75], v[64:65]
	s_nop 0
	v_add_f32_e32 v64, v64, v65
	v_fmamk_f32 v64, v64, 0x3a800000, v206
	v_cmp_gt_f32_e32 vcc, s11, v64
	v_mul_f32_e32 v65, 0x4b800000, v64
	s_nop 0
	v_cndmask_b32_e32 v64, v64, v65, vcc
	v_rsq_f32_e32 v64, v64
	s_nop 0
	v_mul_f32_e32 v65, 0x45800000, v64
	v_cndmask_b32_e32 v64, v64, v65, vcc
	v_pk_mul_f32 v[60:61], v[60:61], v[64:65] op_sel_hi:[1,0]
	s_nop 0
	v_mul_f32_e32 v65, 0xbfb8aa3b, v60
	v_exp_f32_e32 v65, v65
	s_nop 0
	v_add_f32_e32 v65, 1.0, v65
	v_rcp_f32_e32 v66, v65
	v_mul_f32_e32 v65, 0xbfb8aa3b, v61
	v_exp_f32_e32 v65, v65
	s_nop 0
	v_add_f32_e32 v65, 1.0, v65
	v_rcp_f32_e32 v67, v65
	v_pk_mul_f32 v[56:57], v[56:57], v[64:65] op_sel_hi:[1,0]
	v_pk_mul_f32 v[58:59], v[58:59], v[64:65] op_sel_hi:[1,0]
	v_pk_mul_f32 v[52:53], v[52:53], v[64:65] op_sel_hi:[1,0]
	v_pk_mul_f32 v[60:61], v[60:61], v[66:67]
	v_pk_mul_f32 v[48:49], v[48:49], v[64:65] op_sel_hi:[1,0]
	v_pk_mul_f32 v[56:57], v[56:57], v[60:61]
	v_pk_mul_f32 v[60:61], v[62:63], v[64:65] op_sel_hi:[1,0]
	v_cvt_pk_bf16_f32 v56, v56, v57
	v_mul_f32_e32 v62, 0xbfb8aa3b, v60
	v_mul_f32_e32 v63, 0xbfb8aa3b, v61
	v_exp_f32_e32 v62, v62
	v_exp_f32_e32 v63, v63
	v_pk_mul_f32 v[50:51], v[50:51], v[64:65] op_sel_hi:[1,0]
	v_add_f32_e32 v62, 1.0, v62
	v_add_f32_e32 v63, 1.0, v63
	v_rcp_f32_e32 v62, v62
	v_rcp_f32_e32 v63, v63
	s_nop 0
	v_pk_mul_f32 v[60:61], v[60:61], v[62:63]
	s_nop 0
	v_pk_mul_f32 v[58:59], v[58:59], v[60:61]
	s_nop 0
	v_cvt_pk_bf16_f32 v57, v58, v59
	v_mad_i64_i32 v[58:59], s[6:7], v72, s16, v[120:121]
	v_lshl_add_u64 v[58:59], v[58:59], 0, v[122:123]
	global_store_dwordx2 v[58:59], v[56:57], off
	v_mul_f32_e32 v56, 0xbfb8aa3b, v52
	v_mul_f32_e32 v57, 0xbfb8aa3b, v53
	v_exp_f32_e32 v56, v56
	v_exp_f32_e32 v57, v57
	v_add_f32_e32 v56, 1.0, v56
	v_add_f32_e32 v57, 1.0, v57
	v_rcp_f32_e32 v56, v56
	v_rcp_f32_e32 v57, v57
	s_nop 0
	v_pk_mul_f32 v[52:53], v[52:53], v[56:57]
	s_nop 0
	v_pk_mul_f32 v[48:49], v[48:49], v[52:53]
	v_pk_mul_f32 v[52:53], v[54:55], v[64:65] op_sel_hi:[1,0]
	v_add_u32_e32 v56, 0x90, v138
	v_mul_f32_e32 v54, 0xbfb8aa3b, v52
	v_mul_f32_e32 v55, 0xbfb8aa3b, v53
	v_exp_f32_e32 v54, v54
	v_exp_f32_e32 v55, v55
	v_cvt_pk_bf16_f32 v48, v48, v49
	v_ashrrev_i32_e32 v57, 31, v56
	v_add_f32_e32 v54, 1.0, v54
	v_add_f32_e32 v55, 1.0, v55
	v_rcp_f32_e32 v54, v54
	v_rcp_f32_e32 v55, v55
	s_nop 0
	v_pk_mul_f32 v[52:53], v[52:53], v[54:55]
	s_nop 0
	v_pk_mul_f32 v[50:51], v[50:51], v[52:53]
	s_nop 0
	v_cvt_pk_bf16_f32 v49, v50, v51
	global_store_dwordx2 v[58:59], v[48:49], off offset:128
	v_lshlrev_b64 v[48:49], 6, v[56:57]
	v_lshl_add_u64 v[62:63], s[46:47], 0, v[48:49]
	s_waitcnt vmcnt(14)
	v_mov_b64_e32 v[58:59], v[228:229]
	v_mov_b64_e32 v[60:61], v[230:231]
	v_mov_b64_e32 v[48:49], v[232:233]
	v_mov_b64_e32 v[50:51], v[234:235]
	v_mov_b64_e32 v[62:63], v[236:237]
	v_mov_b64_e32 v[64:65], v[238:239]
	v_mov_b64_e32 v[52:53], v[240:241]
	v_mov_b64_e32 v[54:55], v[242:243]
	s_nop 0
	v_mov_b32_e32 v66, v58
	v_mov_b32_e32 v67, v62
	v_mov_b32_e32 v62, v59
	v_pk_add_f32 v[58:59], v[66:67], v[62:63]
	v_mov_b32_e32 v62, v60
	v_mov_b32_e32 v63, v64
	v_mov_b32_e32 v64, v61
	v_pk_add_f32 v[60:61], v[62:63], v[64:65]
	s_nop 0
	v_pk_add_f32 v[58:59], v[58:59], v[60:61]
	v_mov_b32_e32 v60, v48
	v_mov_b32_e32 v61, v52
	v_mov_b32_e32 v52, v49
	v_pk_add_f32 v[48:49], v[60:61], v[52:53]
	v_mov_b32_e32 v52, v50
	v_mov_b32_e32 v53, v54
	v_mov_b32_e32 v54, v51
	v_pk_add_f32 v[50:51], v[52:53], v[54:55]
	s_nop 0
	v_pk_add_f32 v[48:49], v[48:49], v[50:51]
	s_nop 0
	v_pk_add_f32 v[48:49], v[58:59], v[48:49]
	s_nop 0
	v_add_f32_e32 v48, v48, v49
	v_fmamk_f32 v48, v48, 0x3a800000, v206
	v_cmp_gt_f32_e32 vcc, s11, v48
	v_mul_f32_e32 v49, 0x4b800000, v48
	s_nop 0
	v_cndmask_b32_e32 v48, v48, v49, vcc
	v_rsq_f32_e32 v48, v48
	s_nop 0
	v_mul_f32_e32 v49, 0x45800000, v48
	v_cndmask_b32_e32 v48, v48, v49, vcc
	v_pk_mul_f32 v[44:45], v[44:45], v[48:49] op_sel_hi:[1,0]
	s_nop 0
	v_mul_f32_e32 v49, 0xbfb8aa3b, v44
	v_exp_f32_e32 v49, v49
	s_nop 0
	v_add_f32_e32 v49, 1.0, v49
	v_rcp_f32_e32 v50, v49
	v_mul_f32_e32 v49, 0xbfb8aa3b, v45
	v_exp_f32_e32 v49, v49
	s_nop 0
	v_add_f32_e32 v49, 1.0, v49
	v_rcp_f32_e32 v51, v49
	v_pk_mul_f32 v[40:41], v[40:41], v[48:49] op_sel_hi:[1,0]
	v_pk_mul_f32 v[42:43], v[42:43], v[48:49] op_sel_hi:[1,0]
	v_pk_mul_f32 v[36:37], v[36:37], v[48:49] op_sel_hi:[1,0]
	v_pk_mul_f32 v[44:45], v[44:45], v[50:51]
	v_pk_mul_f32 v[32:33], v[32:33], v[48:49] op_sel_hi:[1,0]
	v_pk_mul_f32 v[40:41], v[40:41], v[44:45]
	v_pk_mul_f32 v[44:45], v[46:47], v[48:49] op_sel_hi:[1,0]
	v_cvt_pk_bf16_f32 v40, v40, v41
	v_mul_f32_e32 v46, 0xbfb8aa3b, v44
	v_mul_f32_e32 v47, 0xbfb8aa3b, v45
	v_exp_f32_e32 v46, v46
	v_exp_f32_e32 v47, v47
	v_pk_mul_f32 v[34:35], v[34:35], v[48:49] op_sel_hi:[1,0]
	v_add_f32_e32 v46, 1.0, v46
	v_add_f32_e32 v47, 1.0, v47
	v_rcp_f32_e32 v46, v46
	v_rcp_f32_e32 v47, v47
	s_nop 0
	v_pk_mul_f32 v[44:45], v[44:45], v[46:47]
	s_nop 0
	v_pk_mul_f32 v[42:43], v[42:43], v[44:45]
	s_nop 0
	v_cvt_pk_bf16_f32 v41, v42, v43
	v_mad_i64_i32 v[42:43], s[6:7], v56, s16, v[120:121]
	v_lshl_add_u64 v[42:43], v[42:43], 0, v[122:123]
	global_store_dwordx2 v[42:43], v[40:41], off
	v_mul_f32_e32 v40, 0xbfb8aa3b, v36
	v_mul_f32_e32 v41, 0xbfb8aa3b, v37
	v_exp_f32_e32 v40, v40
	v_exp_f32_e32 v41, v41
	v_add_f32_e32 v40, 1.0, v40
	v_add_f32_e32 v41, 1.0, v41
	v_rcp_f32_e32 v40, v40
	v_rcp_f32_e32 v41, v41
	s_nop 0
	v_pk_mul_f32 v[36:37], v[36:37], v[40:41]
	s_nop 0
	v_pk_mul_f32 v[32:33], v[32:33], v[36:37]
	v_pk_mul_f32 v[36:37], v[38:39], v[48:49] op_sel_hi:[1,0]
	v_add_u32_e32 v40, 0xa0, v138
	v_mul_f32_e32 v38, 0xbfb8aa3b, v36
	v_mul_f32_e32 v39, 0xbfb8aa3b, v37
	v_exp_f32_e32 v38, v38
	v_exp_f32_e32 v39, v39
	v_cvt_pk_bf16_f32 v32, v32, v33
	v_ashrrev_i32_e32 v41, 31, v40
	v_add_f32_e32 v38, 1.0, v38
	v_add_f32_e32 v39, 1.0, v39
	v_rcp_f32_e32 v38, v38
	v_rcp_f32_e32 v39, v39
	s_nop 0
	v_pk_mul_f32 v[36:37], v[36:37], v[38:39]
	s_nop 0
	v_pk_mul_f32 v[34:35], v[34:35], v[36:37]
	s_nop 0
	v_cvt_pk_bf16_f32 v33, v34, v35
	global_store_dwordx2 v[42:43], v[32:33], off offset:128
	v_lshlrev_b64 v[32:33], 6, v[40:41]
	v_lshl_add_u64 v[46:47], s[46:47], 0, v[32:33]
	s_waitcnt vmcnt(10)
	v_mov_b64_e32 v[42:43], v[180:181]
	v_mov_b64_e32 v[44:45], v[182:183]
	v_mov_b64_e32 v[32:33], v[184:185]
	v_mov_b64_e32 v[34:35], v[186:187]
	v_mov_b64_e32 v[46:47], v[188:189]
	v_mov_b64_e32 v[48:49], v[190:191]
	v_mov_b64_e32 v[36:37], v[192:193]
	v_mov_b64_e32 v[38:39], v[194:195]
	s_nop 0
	v_mov_b32_e32 v50, v42
	v_mov_b32_e32 v51, v46
	v_mov_b32_e32 v46, v43
	v_pk_add_f32 v[42:43], v[50:51], v[46:47]
	v_mov_b32_e32 v46, v44
	v_mov_b32_e32 v47, v48
	v_mov_b32_e32 v48, v45
	v_pk_add_f32 v[44:45], v[46:47], v[48:49]
	s_nop 0
	v_pk_add_f32 v[42:43], v[42:43], v[44:45]
	v_mov_b32_e32 v44, v32
	v_mov_b32_e32 v45, v36
	v_mov_b32_e32 v36, v33
	v_pk_add_f32 v[32:33], v[44:45], v[36:37]
	v_mov_b32_e32 v36, v34
	v_mov_b32_e32 v37, v38
	v_mov_b32_e32 v38, v35
	v_pk_add_f32 v[34:35], v[36:37], v[38:39]
	s_nop 0
	v_pk_add_f32 v[32:33], v[32:33], v[34:35]
	s_nop 0
	v_pk_add_f32 v[32:33], v[42:43], v[32:33]
	s_nop 0
	v_add_f32_e32 v32, v32, v33
	v_fmamk_f32 v32, v32, 0x3a800000, v206
	v_cmp_gt_f32_e32 vcc, s11, v32
	v_mul_f32_e32 v33, 0x4b800000, v32
	s_nop 0
	v_cndmask_b32_e32 v32, v32, v33, vcc
	v_rsq_f32_e32 v32, v32
	s_nop 0
	v_mul_f32_e32 v33, 0x45800000, v32
	v_cndmask_b32_e32 v32, v32, v33, vcc
	v_pk_mul_f32 v[28:29], v[28:29], v[32:33] op_sel_hi:[1,0]
	s_nop 0
	v_mul_f32_e32 v33, 0xbfb8aa3b, v28
	v_exp_f32_e32 v33, v33
	s_nop 0
	v_add_f32_e32 v33, 1.0, v33
	v_rcp_f32_e32 v34, v33
	v_mul_f32_e32 v33, 0xbfb8aa3b, v29
	v_exp_f32_e32 v33, v33
	s_nop 0
	v_add_f32_e32 v33, 1.0, v33
	v_rcp_f32_e32 v35, v33
	v_pk_mul_f32 v[24:25], v[24:25], v[32:33] op_sel_hi:[1,0]
	v_pk_mul_f32 v[26:27], v[26:27], v[32:33] op_sel_hi:[1,0]
	v_pk_mul_f32 v[20:21], v[20:21], v[32:33] op_sel_hi:[1,0]
	v_pk_mul_f32 v[28:29], v[28:29], v[34:35]
	v_pk_mul_f32 v[16:17], v[16:17], v[32:33] op_sel_hi:[1,0]
	v_pk_mul_f32 v[24:25], v[24:25], v[28:29]
	v_pk_mul_f32 v[28:29], v[30:31], v[32:33] op_sel_hi:[1,0]
	v_cvt_pk_bf16_f32 v24, v24, v25
	v_mul_f32_e32 v30, 0xbfb8aa3b, v28
	v_mul_f32_e32 v31, 0xbfb8aa3b, v29
	v_exp_f32_e32 v30, v30
	v_exp_f32_e32 v31, v31
	v_pk_mul_f32 v[18:19], v[18:19], v[32:33] op_sel_hi:[1,0]
	v_add_f32_e32 v30, 1.0, v30
	v_add_f32_e32 v31, 1.0, v31
	v_rcp_f32_e32 v30, v30
	v_rcp_f32_e32 v31, v31
	s_nop 0
	v_pk_mul_f32 v[28:29], v[28:29], v[30:31]
	s_nop 0
	v_pk_mul_f32 v[26:27], v[26:27], v[28:29]
	s_nop 0
	v_cvt_pk_bf16_f32 v25, v26, v27
	v_mad_i64_i32 v[26:27], s[6:7], v40, s16, v[120:121]
	v_lshl_add_u64 v[26:27], v[26:27], 0, v[122:123]
	global_store_dwordx2 v[26:27], v[24:25], off
	v_mul_f32_e32 v24, 0xbfb8aa3b, v20
	v_mul_f32_e32 v25, 0xbfb8aa3b, v21
	v_exp_f32_e32 v24, v24
	v_exp_f32_e32 v25, v25
	v_add_f32_e32 v24, 1.0, v24
	v_add_f32_e32 v25, 1.0, v25
	v_rcp_f32_e32 v24, v24
	v_rcp_f32_e32 v25, v25
	s_nop 0
	v_pk_mul_f32 v[20:21], v[20:21], v[24:25]
	s_nop 0
	v_pk_mul_f32 v[16:17], v[16:17], v[20:21]
	v_pk_mul_f32 v[20:21], v[22:23], v[32:33] op_sel_hi:[1,0]
	v_add_u32_e32 v24, 0xb0, v138
	v_mul_f32_e32 v22, 0xbfb8aa3b, v20
	v_mul_f32_e32 v23, 0xbfb8aa3b, v21
	v_exp_f32_e32 v22, v22
	v_exp_f32_e32 v23, v23
	v_cvt_pk_bf16_f32 v16, v16, v17
	v_ashrrev_i32_e32 v25, 31, v24
	v_add_f32_e32 v22, 1.0, v22
	v_add_f32_e32 v23, 1.0, v23
	v_rcp_f32_e32 v22, v22
	v_rcp_f32_e32 v23, v23
	s_nop 0
	v_pk_mul_f32 v[20:21], v[20:21], v[22:23]
	s_nop 0
	v_pk_mul_f32 v[18:19], v[18:19], v[20:21]
	s_nop 0
	v_cvt_pk_bf16_f32 v17, v18, v19
	global_store_dwordx2 v[26:27], v[16:17], off offset:128
	v_lshlrev_b64 v[16:17], 6, v[24:25]
	v_lshl_add_u64 v[30:31], s[46:47], 0, v[16:17]
	s_waitcnt vmcnt(6)
	v_mov_b64_e32 v[26:27], v[196:197]
	v_mov_b64_e32 v[28:29], v[198:199]
	v_mov_b64_e32 v[16:17], v[200:201]
	v_mov_b64_e32 v[18:19], v[202:203]
	v_mov_b64_e32 v[30:31], v[220:221]
	v_mov_b64_e32 v[32:33], v[222:223]
	v_mov_b64_e32 v[20:21], v[244:245]
	v_mov_b64_e32 v[22:23], v[246:247]
	s_nop 0
	v_mov_b32_e32 v34, v26
	v_mov_b32_e32 v35, v30
	v_mov_b32_e32 v30, v27
	v_pk_add_f32 v[26:27], v[34:35], v[30:31]
	v_mov_b32_e32 v30, v28
	v_mov_b32_e32 v31, v32
	v_mov_b32_e32 v32, v29
	v_pk_add_f32 v[28:29], v[30:31], v[32:33]
	s_nop 0
	v_pk_add_f32 v[26:27], v[26:27], v[28:29]
	v_mov_b32_e32 v28, v16
	v_mov_b32_e32 v29, v20
	v_mov_b32_e32 v20, v17
	v_pk_add_f32 v[16:17], v[28:29], v[20:21]
	v_mov_b32_e32 v20, v18
	v_mov_b32_e32 v21, v22
	v_mov_b32_e32 v22, v19
	v_pk_add_f32 v[18:19], v[20:21], v[22:23]
	s_nop 0
	v_pk_add_f32 v[16:17], v[16:17], v[18:19]
	s_nop 0
	v_pk_add_f32 v[16:17], v[26:27], v[16:17]
	s_nop 0
	v_add_f32_e32 v16, v16, v17
	v_fmamk_f32 v16, v16, 0x3a800000, v206
	v_cmp_gt_f32_e32 vcc, s11, v16
	v_mul_f32_e32 v17, 0x4b800000, v16
	s_nop 0
	v_cndmask_b32_e32 v16, v16, v17, vcc
	v_rsq_f32_e32 v16, v16
	s_nop 0
	v_mul_f32_e32 v17, 0x45800000, v16
	v_cndmask_b32_e32 v16, v16, v17, vcc
	v_pk_mul_f32 v[12:13], v[12:13], v[16:17] op_sel_hi:[1,0]
	s_andn2_b64 vcc, exec, s[40:41]
	v_mul_f32_e32 v17, 0xbfb8aa3b, v12
	v_exp_f32_e32 v17, v17
	s_nop 0
	v_add_f32_e32 v17, 1.0, v17
	v_rcp_f32_e32 v18, v17
	v_mul_f32_e32 v17, 0xbfb8aa3b, v13
	v_exp_f32_e32 v17, v17
	s_nop 0
	v_add_f32_e32 v17, 1.0, v17
	v_rcp_f32_e32 v19, v17
	v_pk_mul_f32 v[8:9], v[8:9], v[16:17] op_sel_hi:[1,0]
	v_pk_mul_f32 v[10:11], v[10:11], v[16:17] op_sel_hi:[1,0]
	v_pk_mul_f32 v[4:5], v[4:5], v[16:17] op_sel_hi:[1,0]
	v_pk_mul_f32 v[12:13], v[12:13], v[18:19]
	v_pk_mul_f32 v[0:1], v[0:1], v[16:17] op_sel_hi:[1,0]
	v_pk_mul_f32 v[8:9], v[8:9], v[12:13]
	v_pk_mul_f32 v[12:13], v[14:15], v[16:17] op_sel_hi:[1,0]
	v_cvt_pk_bf16_f32 v8, v8, v9
	v_mul_f32_e32 v14, 0xbfb8aa3b, v12
	v_mul_f32_e32 v15, 0xbfb8aa3b, v13
	v_exp_f32_e32 v14, v14
	v_exp_f32_e32 v15, v15
	v_pk_mul_f32 v[2:3], v[2:3], v[16:17] op_sel_hi:[1,0]
	v_add_f32_e32 v14, 1.0, v14
	v_add_f32_e32 v15, 1.0, v15
	v_rcp_f32_e32 v14, v14
	v_rcp_f32_e32 v15, v15
	s_nop 0
	v_pk_mul_f32 v[12:13], v[12:13], v[14:15]
	s_nop 0
	v_pk_mul_f32 v[10:11], v[10:11], v[12:13]
	s_nop 0
	v_cvt_pk_bf16_f32 v9, v10, v11
	v_mad_i64_i32 v[10:11], s[6:7], v24, s16, v[120:121]
	v_lshl_add_u64 v[10:11], v[10:11], 0, v[122:123]
	global_store_dwordx2 v[10:11], v[8:9], off
	v_mul_f32_e32 v8, 0xbfb8aa3b, v4
	v_mul_f32_e32 v9, 0xbfb8aa3b, v5
	v_exp_f32_e32 v8, v8
	v_exp_f32_e32 v9, v9
	v_add_f32_e32 v8, 1.0, v8
	v_add_f32_e32 v9, 1.0, v9
	v_rcp_f32_e32 v8, v8
	v_rcp_f32_e32 v9, v9
	s_nop 0
	v_pk_mul_f32 v[4:5], v[4:5], v[8:9]
	s_nop 0
	v_pk_mul_f32 v[0:1], v[0:1], v[4:5]
	v_pk_mul_f32 v[4:5], v[6:7], v[16:17] op_sel_hi:[1,0]
	v_cvt_pk_bf16_f32 v0, v0, v1
	v_mul_f32_e32 v6, 0xbfb8aa3b, v4
	v_mul_f32_e32 v7, 0xbfb8aa3b, v5
	v_exp_f32_e32 v6, v6
	v_exp_f32_e32 v7, v7
	v_add_f32_e32 v6, 1.0, v6
	v_add_f32_e32 v7, 1.0, v7
	v_rcp_f32_e32 v6, v6
	v_rcp_f32_e32 v7, v7
	s_nop 0
	v_pk_mul_f32 v[4:5], v[4:5], v[6:7]
	s_nop 0
	v_pk_mul_f32 v[2:3], v[2:3], v[4:5]
	s_nop 0
	v_cvt_pk_bf16_f32 v1, v2, v3
	global_store_dwordx2 v[10:11], v[0:1], off offset:128
	s_cbranch_vccnz .LBB0_1062
	s_andn2_b64 vcc, exec, s[42:43]
	s_cbranch_vccnz .LBB0_1061
	s_barrier
	s_branch .LBB0_1061
